# MLA loop: s_setprio 1 from the first S^T MFMA to the last PV MFMA of every step, 0 over the softmax tail
# speedup vs baseline: 1.0019x; 1.0019x over previous
.LBB0_859:
	ds_read_b128 v[236:239], v214 offset:8192
	ds_read_b128 v[240:243], v215 offset:8192
	ds_read_b128 v[244:247], v216 offset:8192
	ds_read_b128 v[248:251], v217 offset:8192
	ds_read_b128 v[252:255], v218 offset:8192
	ds_read_b128 v[176:179], v219 offset:8192
	v_exp_f32_e32 v97, v97
	v_exp_f32_e32 v99, v99
	v_exp_f32_e32 v100, v100
	v_exp_f32_e32 v101, v101
	v_exp_f32_e32 v102, v102
	v_exp_f32_e32 v103, v103
	v_exp_f32_e32 v106, v106
	v_exp_f32_e32 v107, v107
	s_waitcnt lgkmcnt(4)
	s_setprio 1
	v_mfma_f32_32x32x16_bf16 v[80:95], v[236:239], v[144:147], v[64:79]
	ds_read_b128 v[180:183], v220 offset:8192
	v_exp_f32_e32 v108, v108
	v_exp_f32_e32 v109, v109
	v_exp_f32_e32 v110, v110
	v_exp_f32_e32 v111, v111
	v_mfma_f32_32x32x16_bf16 v[80:95], v[240:243], v[156:159], v[80:95]
	ds_read_b128 v[236:239], v221 offset:8192
	s_add_u32 s98, s34, s60
	s_addc_u32 s99, s35, s59
	s_add_u32 s98, s98, 0x140fc000
	s_addc_u32 s99, s99, 0
	s_add_u32 s100, s34, s62
	s_addc_u32 s101, s35, s61
	s_add_u32 s100, s100, 0x171b0100
	s_addc_u32 s101, s101, 0
	s_mov_b32 m0, s52
	s_cmp_lg_u64 s[24:25], 0
	s_cselect_b32 s4, s100, s98
	s_cselect_b32 s5, s101, s99
	global_load_lds_dwordx4 v190, s[4:5]
	s_mov_b32 m0, s53
	s_cmp_lg_u64 s[26:27], 0
	s_cselect_b32 s4, s100, s98
	s_cselect_b32 s5, s101, s99
	global_load_lds_dwordx4 v192, s[4:5]
	s_mov_b32 m0, s54
	s_cmp_lg_u64 s[28:29], 0
	s_cselect_b32 s4, s100, s98
	s_cselect_b32 s5, s101, s99
	global_load_lds_dwordx4 v194, s[4:5]
	s_mov_b32 m0, s55
	s_cmp_lg_u64 s[30:31], 0
	s_cselect_b32 s4, s100, s98
	s_cselect_b32 s5, s101, s99
	global_load_lds_dwordx4 v196, s[4:5]
	s_mov_b32 m0, s56
	s_cmp_lg_u64 s[6:7], 0
	s_cselect_b32 s4, s100, s98
	s_cselect_b32 s5, s101, s99
	global_load_lds_dwordx4 v198, s[4:5]
	s_waitcnt lgkmcnt(4)
	v_mfma_f32_32x32x16_bf16 v[80:95], v[244:247], v[168:171], v[80:95]
	ds_read_b128 v[240:243], v205 offset:53248
	v_mfma_f32_32x32x16_bf16 v[80:95], v[248:251], v[172:175], v[80:95]
	ds_read_b128 v[244:247], v207 offset:53248
	s_waitcnt lgkmcnt(4)
	v_mfma_f32_32x32x16_bf16 v[80:95], v[252:255], v[164:167], v[80:95]
	ds_read_b128 v[248:251], v209 offset:53248
	v_mfma_f32_32x32x16_bf16 v[80:95], v[176:179], v[160:163], v[80:95]
	ds_read_b128 v[252:255], v211 offset:53248
	s_waitcnt lgkmcnt(4)
	v_mfma_f32_32x32x16_bf16 v[80:95], v[180:183], v[152:155], v[80:95]
	ds_read_b128 v[176:179], v225
	v_mfma_f32_32x32x16_bf16 v[80:95], v[236:239], v[148:151], v[80:95]
	ds_read_b128 v[180:183], v225 offset:4096
	s_waitcnt lgkmcnt(4)
	v_mfma_f32_32x32x16_bf16 v[80:95], v[240:243], v[140:143], v[80:95]
	ds_read_b128 v[236:239], v225 offset:8192
	v_mfma_f32_32x32x16_bf16 v[80:95], v[244:247], v[136:139], v[80:95]
	ds_read_b128 v[240:243], v225 offset:12288
	s_waitcnt lgkmcnt(4)
	v_mfma_f32_32x32x16_bf16 v[80:95], v[248:251], v[132:135], v[80:95]
	ds_read_b128 v[244:247], v226
	v_mfma_f32_32x32x16_bf16 v[80:95], v[252:255], v[128:131], v[80:95]
	ds_read_b128 v[248:251], v226 offset:4096
	v_exp_f32_e32 v112, v96
	v_exp_f32_e32 v113, v98
	v_exp_f32_e32 v114, v104
	v_exp_f32_e32 v115, v105
	v_add_f32_e32 v96, 0, v112
	v_add_f32_e32 v96, v97, v96
	v_add_f32_e32 v96, v113, v96
	v_add_f32_e32 v96, v99, v96
	v_add_f32_e32 v96, v100, v96
	v_add_f32_e32 v96, v101, v96
	v_add_f32_e32 v96, v102, v96
	v_add_f32_e32 v96, v103, v96
	v_cvt_pk_bf16_f32 v100, v100, v101
	v_cvt_pk_bf16_f32 v101, v102, v103
	v_cvt_pk_bf16_f32 v98, v112, v97
	v_cvt_pk_bf16_f32 v99, v113, v99
	v_max_f32_e32 v97, v81, v81
	v_add_f32_e32 v96, v114, v96
	s_waitcnt lgkmcnt(4)
	v_mfma_f32_32x32x16_bf16 v[48:63], v[176:179], v[98:101], v[48:63]
	ds_read_b128 v[252:255], v226 offset:8192
	v_add_f32_e32 v96, v115, v96
	v_add_f32_e32 v96, v106, v96
	v_add_f32_e32 v96, v107, v96
	v_add_f32_e32 v96, v108, v96
	v_add_f32_e32 v96, v109, v96
	v_add_f32_e32 v96, v110, v96
	v_mfma_f32_32x32x16_bf16 v[32:47], v[180:183], v[98:101], v[32:47]
	ds_read_b128 v[176:179], v226 offset:12288
	v_add_f32_e32 v96, v111, v96
	v_add_f32_e32 v112, v230, v96
	s_waitcnt lgkmcnt(4)
	v_mfma_f32_32x32x16_bf16 v[16:31], v[236:239], v[98:101], v[16:31]
	ds_read_b128 v[180:183], v214 offset:16384
	v_mfma_f32_32x32x16_bf16 v[0:15], v[240:243], v[98:101], v[0:15]
	ds_read_b128 v[236:239], v215 offset:16384
	v_cvt_pk_bf16_f32 v98, v114, v115
	v_cvt_pk_bf16_f32 v99, v106, v107
	v_cvt_pk_bf16_f32 v100, v108, v109
	v_cvt_pk_bf16_f32 v101, v110, v111
	s_nop 0
	s_waitcnt lgkmcnt(4)
	v_mfma_f32_32x32x16_bf16 v[48:63], v[244:247], v[98:101], v[48:63]
	ds_read_b128 v[240:243], v216 offset:16384
	v_mfma_f32_32x32x16_bf16 v[32:47], v[248:251], v[98:101], v[32:47]
	ds_read_b128 v[244:247], v217 offset:16384
	s_waitcnt lgkmcnt(4)
	v_mfma_f32_32x32x16_bf16 v[16:31], v[252:255], v[98:101], v[16:31]
	ds_read_b128 v[248:251], v218 offset:16384
	v_mfma_f32_32x32x16_bf16 v[0:15], v[176:179], v[98:101], v[0:15]
	s_setprio 0
	ds_read_b128 v[252:255], v219 offset:16384
	v_max_f32_e32 v98, v80, v80
	v_max_f32_e32 v97, v98, v97
	v_max3_f32 v97, v97, v82, v83
	v_max3_f32 v97, v97, v84, v85
	v_max3_f32 v97, v97, v86, v87
	v_max3_f32 v97, v97, v88, v89
	v_max3_f32 v97, v97, v90, v91
	v_max3_f32 v97, v97, v92, v93
	v_max3_f32 v97, v97, v94, v95
	ds_bpermute_b32 v98, v229, v97
	s_waitcnt lgkmcnt(0)
	v_max_f32_e32 v96, v98, v98
	v_max_f32_e32 v96, v97, v96
	v_cmp_lt_f32_e32 vcc, 0, v96
	s_cbranch_vccz .LBB0_861
	v_max_f32_e32 v96, v96, v96
	v_max_f32_e32 v96, 0, v96
	v_exp_f32_e64 v98, -v96
	v_pk_add_f32 v[80:81], v[80:81], v[96:97] op_sel_hi:[1,0] neg_lo:[0,1] neg_hi:[0,1]
	v_pk_add_f32 v[82:83], v[82:83], v[96:97] op_sel_hi:[1,0] neg_lo:[0,1] neg_hi:[0,1]
	v_pk_add_f32 v[84:85], v[84:85], v[96:97] op_sel_hi:[1,0] neg_lo:[0,1] neg_hi:[0,1]
	v_mul_f32_e32 v112, v112, v98
	v_pk_add_f32 v[86:87], v[86:87], v[96:97] op_sel_hi:[1,0] neg_lo:[0,1] neg_hi:[0,1]
	v_pk_add_f32 v[88:89], v[88:89], v[96:97] op_sel_hi:[1,0] neg_lo:[0,1] neg_hi:[0,1]
	v_pk_add_f32 v[90:91], v[90:91], v[96:97] op_sel_hi:[1,0] neg_lo:[0,1] neg_hi:[0,1]
	v_pk_add_f32 v[92:93], v[92:93], v[96:97] op_sel_hi:[1,0] neg_lo:[0,1] neg_hi:[0,1]
	v_sub_f32_e32 v79, v79, v96
	v_sub_f32_e32 v78, v78, v96
	v_sub_f32_e32 v77, v77, v96
	v_sub_f32_e32 v76, v76, v96
	v_sub_f32_e32 v75, v75, v96
	v_sub_f32_e32 v74, v74, v96
	v_sub_f32_e32 v73, v73, v96
	v_sub_f32_e32 v72, v72, v96
	v_sub_f32_e32 v71, v71, v96
	v_sub_f32_e32 v70, v70, v96
	v_sub_f32_e32 v69, v69, v96
	v_sub_f32_e32 v68, v68, v96
	v_sub_f32_e32 v67, v67, v96
	v_sub_f32_e32 v66, v66, v96
	v_sub_f32_e32 v65, v65, v96
	v_sub_f32_e32 v64, v64, v96
	v_pk_add_f32 v[94:95], v[94:95], v[96:97] op_sel_hi:[1,0] neg_lo:[0,1] neg_hi:[0,1]
	v_pk_mul_f32 v[62:63], v[62:63], v[98:99] op_sel_hi:[1,0]
	v_pk_mul_f32 v[60:61], v[60:61], v[98:99] op_sel_hi:[1,0]
	v_pk_mul_f32 v[58:59], v[58:59], v[98:99] op_sel_hi:[1,0]
	v_pk_mul_f32 v[56:57], v[56:57], v[98:99] op_sel_hi:[1,0]
	v_pk_mul_f32 v[54:55], v[54:55], v[98:99] op_sel_hi:[1,0]
	v_pk_mul_f32 v[52:53], v[52:53], v[98:99] op_sel_hi:[1,0]
	v_pk_mul_f32 v[50:51], v[50:51], v[98:99] op_sel_hi:[1,0]
	v_pk_mul_f32 v[48:49], v[48:49], v[98:99] op_sel_hi:[1,0]
	v_pk_mul_f32 v[46:47], v[46:47], v[98:99] op_sel_hi:[1,0]
	v_pk_mul_f32 v[44:45], v[44:45], v[98:99] op_sel_hi:[1,0]
	v_pk_mul_f32 v[42:43], v[42:43], v[98:99] op_sel_hi:[1,0]
	v_pk_mul_f32 v[40:41], v[40:41], v[98:99] op_sel_hi:[1,0]
	v_pk_mul_f32 v[38:39], v[38:39], v[98:99] op_sel_hi:[1,0]
	v_pk_mul_f32 v[36:37], v[36:37], v[98:99] op_sel_hi:[1,0]
	v_pk_mul_f32 v[34:35], v[34:35], v[98:99] op_sel_hi:[1,0]
	v_pk_mul_f32 v[32:33], v[32:33], v[98:99] op_sel_hi:[1,0]
	v_pk_mul_f32 v[30:31], v[30:31], v[98:99] op_sel_hi:[1,0]
	v_pk_mul_f32 v[28:29], v[28:29], v[98:99] op_sel_hi:[1,0]
	v_pk_mul_f32 v[26:27], v[26:27], v[98:99] op_sel_hi:[1,0]
	v_pk_mul_f32 v[24:25], v[24:25], v[98:99] op_sel_hi:[1,0]
	v_pk_mul_f32 v[22:23], v[22:23], v[98:99] op_sel_hi:[1,0]
	v_pk_mul_f32 v[20:21], v[20:21], v[98:99] op_sel_hi:[1,0]
	v_pk_mul_f32 v[18:19], v[18:19], v[98:99] op_sel_hi:[1,0]
	v_pk_mul_f32 v[16:17], v[16:17], v[98:99] op_sel_hi:[1,0]
	v_pk_mul_f32 v[14:15], v[14:15], v[98:99] op_sel_hi:[1,0]
	v_pk_mul_f32 v[12:13], v[12:13], v[98:99] op_sel_hi:[1,0]
	v_pk_mul_f32 v[10:11], v[10:11], v[98:99] op_sel_hi:[1,0]
	v_pk_mul_f32 v[8:9], v[8:9], v[98:99] op_sel_hi:[1,0]
	v_pk_mul_f32 v[6:7], v[6:7], v[98:99] op_sel_hi:[1,0]
	v_pk_mul_f32 v[4:5], v[4:5], v[98:99] op_sel_hi:[1,0]
	v_pk_mul_f32 v[2:3], v[2:3], v[98:99] op_sel_hi:[1,0]
	v_pk_mul_f32 v[0:1], v[0:1], v[98:99] op_sel_hi:[1,0]
.LBB0_861:
	v_exp_f32_e32 v113, v80
	v_exp_f32_e32 v122, v81
	v_exp_f32_e32 v123, v82
	s_setprio 1
	v_mfma_f32_32x32x16_bf16 v[96:111], v[180:183], v[144:147], v[64:79]
	ds_read_b128 v[176:179], v220 offset:16384
	v_exp_f32_e32 v124, v83
	v_exp_f32_e32 v125, v84
	v_exp_f32_e32 v126, v85
	v_exp_f32_e32 v127, v86
	v_exp_f32_e32 v230, v87
	v_exp_f32_e32 v88, v88
	v_exp_f32_e32 v89, v89
	v_mfma_f32_32x32x16_bf16 v[96:111], v[236:239], v[156:159], v[96:111]
	ds_read_b128 v[180:183], v221 offset:16384
	v_exp_f32_e32 v90, v90
	v_exp_f32_e32 v91, v91
	v_exp_f32_e32 v92, v92
	v_exp_f32_e32 v93, v93
	v_exp_f32_e32 v94, v94
	v_exp_f32_e32 v95, v95
	v_mfma_f32_32x32x16_bf16 v[96:111], v[240:243], v[168:171], v[96:111]
	ds_read_b128 v[236:239], v205 offset:57344
	v_mfma_f32_32x32x16_bf16 v[96:111], v[244:247], v[172:175], v[96:111]
	ds_read_b128 v[240:243], v207 offset:57344
	v_mfma_f32_32x32x16_bf16 v[96:111], v[248:251], v[164:167], v[96:111]
	ds_read_b128 v[244:247], v209 offset:57344
	v_mfma_f32_32x32x16_bf16 v[96:111], v[252:255], v[160:163], v[96:111]
	ds_read_b128 v[248:251], v211 offset:57344
	s_waitcnt lgkmcnt(4)
	v_mfma_f32_32x32x16_bf16 v[96:111], v[176:179], v[152:155], v[96:111]
	ds_read_b128 v[252:255], v227
	v_mfma_f32_32x32x16_bf16 v[96:111], v[180:183], v[148:151], v[96:111]
	ds_read_b128 v[176:179], v227 offset:4096
	s_waitcnt lgkmcnt(4)
	v_mfma_f32_32x32x16_bf16 v[96:111], v[236:239], v[140:143], v[96:111]
	ds_read_b128 v[180:183], v227 offset:8192
	v_mfma_f32_32x32x16_bf16 v[96:111], v[240:243], v[136:139], v[96:111]
	ds_read_b128 v[236:239], v227 offset:12288
	s_waitcnt lgkmcnt(4)
	v_mfma_f32_32x32x16_bf16 v[96:111], v[244:247], v[132:135], v[96:111]
	ds_read_b128 v[240:243], v228 offset:4096
	v_cvt_pk_bf16_f32 v114, v113, v122
	v_cvt_pk_bf16_f32 v115, v123, v124
	v_cvt_pk_bf16_f32 v116, v125, v126
	v_cvt_pk_bf16_f32 v117, v127, v230
	v_mfma_f32_32x32x16_bf16 v[96:111], v[248:251], v[128:131], v[96:111]
	ds_read_b128 v[244:247], v228
	v_add_f32_e32 v118, 0, v113
	v_add_f32_e32 v113, v122, v118
	v_add_f32_e32 v113, v123, v113
	s_waitcnt lgkmcnt(4)
	v_mfma_f32_32x32x16_bf16 v[48:63], v[252:255], v[114:117], v[48:63]
	ds_read_b128 v[248:251], v228 offset:8192
	v_add_f32_e32 v80, v124, v113
	v_add_f32_e32 v80, v125, v80
	v_add_f32_e32 v80, v126, v80
	v_add_f32_e32 v113, v127, v80
	v_mfma_f32_32x32x16_bf16 v[32:47], v[176:179], v[114:117], v[32:47]
	ds_read_b128 v[252:255], v228 offset:12288
	v_add_f32_e32 v84, v230, v113
	v_add_f32_e32 v84, v88, v84
	v_add_f32_e32 v113, v89, v84
	s_waitcnt lgkmcnt(4)
	v_mfma_f32_32x32x16_bf16 v[16:31], v[180:183], v[114:117], v[16:31]
	ds_read_b128 v[176:179], v214 offset:24576
	v_add_f32_e32 v80, v90, v113
	v_add_f32_e32 v80, v91, v80
	v_add_f32_e32 v80, v92, v80
	v_add_f32_e32 v113, v93, v80
	v_add_f32_e32 v113, v94, v113
	v_mfma_f32_32x32x16_bf16 v[0:15], v[236:239], v[114:117], v[0:15]
	ds_read_b128 v[180:183], v215 offset:24576
	v_cvt_pk_bf16_f32 v84, v88, v89
	v_cvt_pk_bf16_f32 v85, v90, v91
	v_cvt_pk_bf16_f32 v86, v92, v93
	v_max_f32_e32 v92, v97, v97
	v_max_f32_e32 v93, v96, v96
	v_max_f32_e32 v92, v93, v92
	v_max3_f32 v92, v92, v98, v99
	v_max3_f32 v92, v92, v100, v101
	v_cvt_pk_bf16_f32 v87, v94, v95
	v_max3_f32 v92, v92, v102, v103
	v_add_f32_e32 v94, v95, v113
	s_waitcnt lgkmcnt(4)
	v_mfma_f32_32x32x16_bf16 v[32:47], v[240:243], v[84:87], v[32:47]
	ds_read_b128 v[236:239], v216 offset:24576
	v_max3_f32 v88, v92, v104, v105
	v_max3_f32 v88, v88, v106, v107
	v_max3_f32 v88, v88, v108, v109
	v_max3_f32 v92, v88, v110, v111
	ds_bpermute_b32 v93, v229, v92
	v_add_f32_e32 v112, v112, v94
	v_mfma_f32_32x32x16_bf16 v[48:63], v[244:247], v[84:87], v[48:63]
	ds_read_b128 v[240:243], v217 offset:24576
	s_waitcnt vmcnt(0)
	s_barrier
	s_waitcnt lgkmcnt(5)
	v_mfma_f32_32x32x16_bf16 v[16:31], v[248:251], v[84:87], v[16:31]
	ds_read_b128 v[244:247], v218 offset:24576
	s_waitcnt lgkmcnt(2)
	v_max_f32_e32 v80, v93, v93
	v_max_f32_e32 v80, v92, v80
	v_cmp_lt_f32_e32 vcc, 0, v80
	v_mfma_f32_32x32x16_bf16 v[0:15], v[252:255], v[84:87], v[0:15]
	s_setprio 0
	ds_read_b128 v[248:251], v219 offset:24576
	s_cbranch_vccz .LBB0_863
	v_max_f32_e32 v80, v80, v80
	v_max_f32_e32 v80, 0, v80
	v_exp_f32_e64 v82, -v80
	v_pk_add_f32 v[96:97], v[96:97], v[80:81] op_sel_hi:[1,0] neg_lo:[0,1] neg_hi:[0,1]
	v_pk_add_f32 v[98:99], v[98:99], v[80:81] op_sel_hi:[1,0] neg_lo:[0,1] neg_hi:[0,1]
	v_pk_add_f32 v[100:101], v[100:101], v[80:81] op_sel_hi:[1,0] neg_lo:[0,1] neg_hi:[0,1]
	v_mul_f32_e32 v112, v112, v82
	v_pk_add_f32 v[102:103], v[102:103], v[80:81] op_sel_hi:[1,0] neg_lo:[0,1] neg_hi:[0,1]
	v_pk_add_f32 v[104:105], v[104:105], v[80:81] op_sel_hi:[1,0] neg_lo:[0,1] neg_hi:[0,1]
	v_pk_add_f32 v[106:107], v[106:107], v[80:81] op_sel_hi:[1,0] neg_lo:[0,1] neg_hi:[0,1]
	v_pk_add_f32 v[108:109], v[108:109], v[80:81] op_sel_hi:[1,0] neg_lo:[0,1] neg_hi:[0,1]
	v_sub_f32_e32 v79, v79, v80
	v_sub_f32_e32 v78, v78, v80
	v_sub_f32_e32 v77, v77, v80
	v_sub_f32_e32 v76, v76, v80
	v_sub_f32_e32 v75, v75, v80
	v_sub_f32_e32 v74, v74, v80
	v_sub_f32_e32 v73, v73, v80
	v_sub_f32_e32 v72, v72, v80
	v_sub_f32_e32 v71, v71, v80
	v_sub_f32_e32 v70, v70, v80
	v_sub_f32_e32 v69, v69, v80
	v_sub_f32_e32 v68, v68, v80
	v_sub_f32_e32 v67, v67, v80
	v_sub_f32_e32 v66, v66, v80
	v_sub_f32_e32 v65, v65, v80
	v_sub_f32_e32 v64, v64, v80
	v_pk_add_f32 v[110:111], v[110:111], v[80:81] op_sel_hi:[1,0] neg_lo:[0,1] neg_hi:[0,1]
	v_pk_mul_f32 v[62:63], v[62:63], v[82:83] op_sel_hi:[1,0]
	v_pk_mul_f32 v[60:61], v[60:61], v[82:83] op_sel_hi:[1,0]
	v_pk_mul_f32 v[58:59], v[58:59], v[82:83] op_sel_hi:[1,0]
	v_pk_mul_f32 v[56:57], v[56:57], v[82:83] op_sel_hi:[1,0]
	v_pk_mul_f32 v[54:55], v[54:55], v[82:83] op_sel_hi:[1,0]
	v_pk_mul_f32 v[52:53], v[52:53], v[82:83] op_sel_hi:[1,0]
	v_pk_mul_f32 v[50:51], v[50:51], v[82:83] op_sel_hi:[1,0]
	v_pk_mul_f32 v[48:49], v[48:49], v[82:83] op_sel_hi:[1,0]
	v_pk_mul_f32 v[46:47], v[46:47], v[82:83] op_sel_hi:[1,0]
	v_pk_mul_f32 v[44:45], v[44:45], v[82:83] op_sel_hi:[1,0]
	v_pk_mul_f32 v[42:43], v[42:43], v[82:83] op_sel_hi:[1,0]
	v_pk_mul_f32 v[40:41], v[40:41], v[82:83] op_sel_hi:[1,0]
	v_pk_mul_f32 v[38:39], v[38:39], v[82:83] op_sel_hi:[1,0]
	v_pk_mul_f32 v[36:37], v[36:37], v[82:83] op_sel_hi:[1,0]
	v_pk_mul_f32 v[34:35], v[34:35], v[82:83] op_sel_hi:[1,0]
	v_pk_mul_f32 v[32:33], v[32:33], v[82:83] op_sel_hi:[1,0]
	v_pk_mul_f32 v[30:31], v[30:31], v[82:83] op_sel_hi:[1,0]
	v_pk_mul_f32 v[28:29], v[28:29], v[82:83] op_sel_hi:[1,0]
	v_pk_mul_f32 v[26:27], v[26:27], v[82:83] op_sel_hi:[1,0]
	v_pk_mul_f32 v[24:25], v[24:25], v[82:83] op_sel_hi:[1,0]
	v_pk_mul_f32 v[22:23], v[22:23], v[82:83] op_sel_hi:[1,0]
	v_pk_mul_f32 v[20:21], v[20:21], v[82:83] op_sel_hi:[1,0]
	v_pk_mul_f32 v[18:19], v[18:19], v[82:83] op_sel_hi:[1,0]
	v_pk_mul_f32 v[16:17], v[16:17], v[82:83] op_sel_hi:[1,0]
	v_pk_mul_f32 v[14:15], v[14:15], v[82:83] op_sel_hi:[1,0]
	v_pk_mul_f32 v[12:13], v[12:13], v[82:83] op_sel_hi:[1,0]
	v_pk_mul_f32 v[10:11], v[10:11], v[82:83] op_sel_hi:[1,0]
	v_pk_mul_f32 v[8:9], v[8:9], v[82:83] op_sel_hi:[1,0]
	v_pk_mul_f32 v[6:7], v[6:7], v[82:83] op_sel_hi:[1,0]
	v_pk_mul_f32 v[4:5], v[4:5], v[82:83] op_sel_hi:[1,0]
	v_pk_mul_f32 v[2:3], v[2:3], v[82:83] op_sel_hi:[1,0]
	v_pk_mul_f32 v[0:1], v[0:1], v[82:83] op_sel_hi:[1,0]
.LBB0_863:
	v_exp_f32_e32 v96, v96
	v_exp_f32_e32 v97, v97
	v_exp_f32_e32 v98, v98
	s_setprio 1
	v_mfma_f32_32x32x16_bf16 v[80:95], v[176:179], v[144:147], v[64:79]
	ds_read_b128 v[252:255], v220 offset:24576
	v_exp_f32_e32 v99, v99
	v_exp_f32_e32 v100, v100
	v_exp_f32_e32 v101, v101
	v_exp_f32_e32 v102, v102
	v_exp_f32_e32 v103, v103
	v_cvt_pk_bf16_f32 v122, v96, v97
	v_cvt_pk_bf16_f32 v123, v98, v99
	v_mfma_f32_32x32x16_bf16 v[80:95], v[180:183], v[156:159], v[80:95]
	ds_read_b128 v[176:179], v221 offset:24576
	s_add_i32 s4, s8, 3
	s_cmp_ge_u32 s4, s9
	s_cbranch_scc1 .Lmla_dma_skip_t1
	s_add_u32 s98, s34, s60
	s_addc_u32 s99, s35, s59
	s_add_u32 s98, s98, 0x14102000
	s_addc_u32 s99, s99, 0
	s_add_u32 s100, s34, s62
	s_addc_u32 s101, s35, s61
	s_add_u32 s100, s100, 0x171b0180
	s_addc_u32 s101, s101, 0
	s_mov_b32 m0, s41
	s_cmp_lg_u64 s[24:25], 0
	s_cselect_b32 s4, s100, s98
	s_cselect_b32 s5, s101, s99
	global_load_lds_dwordx4 v190, s[4:5]
	s_mov_b32 m0, s42
	s_cmp_lg_u64 s[26:27], 0
	s_cselect_b32 s4, s100, s98
	s_cselect_b32 s5, s101, s99
	global_load_lds_dwordx4 v192, s[4:5]
	s_mov_b32 m0, s43
	s_cmp_lg_u64 s[28:29], 0
	s_cselect_b32 s4, s100, s98
	s_cselect_b32 s5, s101, s99
	global_load_lds_dwordx4 v194, s[4:5]
	s_mov_b32 m0, s44
	s_cmp_lg_u64 s[30:31], 0
	s_cselect_b32 s4, s100, s98
	s_cselect_b32 s5, s101, s99
	global_load_lds_dwordx4 v196, s[4:5]
	s_mov_b32 m0, s45
	s_cmp_lg_u64 s[6:7], 0
	s_cselect_b32 s4, s100, s98
	s_cselect_b32 s5, s101, s99
	global_load_lds_dwordx4 v198, s[4:5]

.LBB0_867:
	v_exp_f32_e32 v113, v80
	v_exp_f32_e32 v122, v81
	v_exp_f32_e32 v123, v82
	s_setprio 1
	v_mfma_f32_32x32x16_bf16 v[96:111], v[252:255], v[144:147], v[64:79]
	ds_read_b128 v[248:251], v220 offset:32768
	v_exp_f32_e32 v124, v83
	v_exp_f32_e32 v125, v84
	v_exp_f32_e32 v126, v85
	v_exp_f32_e32 v127, v86
	v_exp_f32_e32 v230, v87
	v_exp_f32_e32 v88, v88
	v_exp_f32_e32 v89, v89
	v_mfma_f32_32x32x16_bf16 v[96:111], v[176:179], v[156:159], v[96:111]
	ds_read_b128 v[252:255], v221 offset:32768
	v_exp_f32_e32 v90, v90
	v_exp_f32_e32 v91, v91
	v_exp_f32_e32 v92, v92
	v_exp_f32_e32 v93, v93
	v_exp_f32_e32 v94, v94
	v_exp_f32_e32 v95, v95
	v_mfma_f32_32x32x16_bf16 v[96:111], v[180:183], v[168:171], v[96:111]
	ds_read_b128 v[176:179], v206 offset:16384
	v_mfma_f32_32x32x16_bf16 v[96:111], v[236:239], v[172:175], v[96:111]
	ds_read_b128 v[180:183], v208 offset:16384
	v_mfma_f32_32x32x16_bf16 v[96:111], v[240:243], v[164:167], v[96:111]
	ds_read_b128 v[236:239], v210 offset:16384
	s_waitcnt lgkmcnt(4)
	v_mfma_f32_32x32x16_bf16 v[96:111], v[244:247], v[160:163], v[96:111]
	ds_read_b128 v[240:243], v212 offset:16384
	v_mfma_f32_32x32x16_bf16 v[96:111], v[248:251], v[152:155], v[96:111]
	ds_read_b128 v[244:247], v227 offset:16384
	s_waitcnt lgkmcnt(4)
	v_mfma_f32_32x32x16_bf16 v[96:111], v[252:255], v[148:151], v[96:111]
	ds_read_b128 v[248:251], v227 offset:20480
	v_mfma_f32_32x32x16_bf16 v[96:111], v[176:179], v[140:143], v[96:111]
	ds_read_b128 v[252:255], v227 offset:24576
	s_waitcnt lgkmcnt(4)
	v_mfma_f32_32x32x16_bf16 v[96:111], v[180:183], v[136:139], v[96:111]
	ds_read_b128 v[176:179], v227 offset:28672
	v_mfma_f32_32x32x16_bf16 v[96:111], v[236:239], v[132:135], v[96:111]
	ds_read_b128 v[180:183], v228 offset:20480
	v_cvt_pk_bf16_f32 v114, v113, v122
	v_cvt_pk_bf16_f32 v115, v123, v124
	v_cvt_pk_bf16_f32 v116, v125, v126
	v_cvt_pk_bf16_f32 v117, v127, v230
	s_waitcnt lgkmcnt(4)
	v_mfma_f32_32x32x16_bf16 v[96:111], v[240:243], v[128:131], v[96:111]
	ds_read_b128 v[236:239], v228 offset:16384
	v_add_f32_e32 v118, 0, v113
	v_add_f32_e32 v113, v122, v118
	v_add_f32_e32 v113, v123, v113
	v_mfma_f32_32x32x16_bf16 v[48:63], v[244:247], v[114:117], v[48:63]
	ds_read_b128 v[240:243], v228 offset:24576
	v_add_f32_e32 v80, v124, v113
	v_add_f32_e32 v80, v125, v80
	v_add_f32_e32 v80, v126, v80
	v_add_f32_e32 v113, v127, v80
	s_waitcnt lgkmcnt(4)
	v_mfma_f32_32x32x16_bf16 v[32:47], v[248:251], v[114:117], v[32:47]
	ds_read_b128 v[244:247], v228 offset:28672
	v_add_f32_e32 v84, v230, v113
	v_add_f32_e32 v84, v88, v84
	v_add_f32_e32 v113, v89, v84
	v_mfma_f32_32x32x16_bf16 v[16:31], v[252:255], v[114:117], v[16:31]
	ds_read_b128 v[248:251], v214 offset:40960
	v_add_f32_e32 v80, v90, v113
	v_add_f32_e32 v80, v91, v80
	v_add_f32_e32 v80, v92, v80
	v_add_f32_e32 v113, v93, v80
	v_add_f32_e32 v113, v94, v113
	s_waitcnt lgkmcnt(4)
	v_mfma_f32_32x32x16_bf16 v[0:15], v[176:179], v[114:117], v[0:15]
	ds_read_b128 v[252:255], v215 offset:40960
	v_cvt_pk_bf16_f32 v84, v88, v89
	v_cvt_pk_bf16_f32 v85, v90, v91
	v_cvt_pk_bf16_f32 v86, v92, v93
	v_max_f32_e32 v92, v97, v97
	v_max_f32_e32 v93, v96, v96
	v_max_f32_e32 v92, v93, v92
	v_max3_f32 v92, v92, v98, v99
	v_max3_f32 v92, v92, v100, v101
	v_cvt_pk_bf16_f32 v87, v94, v95
	v_max3_f32 v92, v92, v102, v103
	v_add_f32_e32 v94, v95, v113
	v_mfma_f32_32x32x16_bf16 v[32:47], v[180:183], v[84:87], v[32:47]
	ds_read_b128 v[176:179], v216 offset:40960
	v_max3_f32 v88, v92, v104, v105
	v_max3_f32 v88, v88, v106, v107
	v_max3_f32 v88, v88, v108, v109
	v_max3_f32 v92, v88, v110, v111
	ds_bpermute_b32 v93, v229, v92
	v_add_f32_e32 v112, v112, v94
	s_waitcnt lgkmcnt(5)
	v_mfma_f32_32x32x16_bf16 v[48:63], v[236:239], v[84:87], v[48:63]
	ds_read_b128 v[180:183], v217 offset:40960
	s_waitcnt vmcnt(0)
	s_barrier
	v_mfma_f32_32x32x16_bf16 v[16:31], v[240:243], v[84:87], v[16:31]
	ds_read_b128 v[236:239], v218 offset:40960
	s_waitcnt lgkmcnt(2)
	v_max_f32_e32 v80, v93, v93
	v_max_f32_e32 v80, v92, v80
	v_cmp_lt_f32_e32 vcc, 0, v80
	v_mfma_f32_32x32x16_bf16 v[0:15], v[244:247], v[84:87], v[0:15]
	s_setprio 0
	ds_read_b128 v[240:243], v219 offset:40960
	s_cbranch_vccz .LBB0_869
	v_max_f32_e32 v80, v80, v80
	v_max_f32_e32 v80, 0, v80
	v_exp_f32_e64 v82, -v80
	v_pk_add_f32 v[96:97], v[96:97], v[80:81] op_sel_hi:[1,0] neg_lo:[0,1] neg_hi:[0,1]
	v_pk_add_f32 v[98:99], v[98:99], v[80:81] op_sel_hi:[1,0] neg_lo:[0,1] neg_hi:[0,1]
	v_pk_add_f32 v[100:101], v[100:101], v[80:81] op_sel_hi:[1,0] neg_lo:[0,1] neg_hi:[0,1]
	v_mul_f32_e32 v112, v112, v82
	v_pk_add_f32 v[102:103], v[102:103], v[80:81] op_sel_hi:[1,0] neg_lo:[0,1] neg_hi:[0,1]
	v_pk_add_f32 v[104:105], v[104:105], v[80:81] op_sel_hi:[1,0] neg_lo:[0,1] neg_hi:[0,1]
	v_pk_add_f32 v[106:107], v[106:107], v[80:81] op_sel_hi:[1,0] neg_lo:[0,1] neg_hi:[0,1]
	v_pk_add_f32 v[108:109], v[108:109], v[80:81] op_sel_hi:[1,0] neg_lo:[0,1] neg_hi:[0,1]
	v_sub_f32_e32 v79, v79, v80
	v_sub_f32_e32 v78, v78, v80
	v_sub_f32_e32 v77, v77, v80
	v_sub_f32_e32 v76, v76, v80
	v_sub_f32_e32 v75, v75, v80
	v_sub_f32_e32 v74, v74, v80
	v_sub_f32_e32 v73, v73, v80
	v_sub_f32_e32 v72, v72, v80
	v_sub_f32_e32 v71, v71, v80
	v_sub_f32_e32 v70, v70, v80
	v_sub_f32_e32 v69, v69, v80
	v_sub_f32_e32 v68, v68, v80
	v_sub_f32_e32 v67, v67, v80
	v_sub_f32_e32 v66, v66, v80
	v_sub_f32_e32 v65, v65, v80
	v_sub_f32_e32 v64, v64, v80
	v_pk_add_f32 v[110:111], v[110:111], v[80:81] op_sel_hi:[1,0] neg_lo:[0,1] neg_hi:[0,1]
	v_pk_mul_f32 v[62:63], v[62:63], v[82:83] op_sel_hi:[1,0]
	v_pk_mul_f32 v[60:61], v[60:61], v[82:83] op_sel_hi:[1,0]
	v_pk_mul_f32 v[58:59], v[58:59], v[82:83] op_sel_hi:[1,0]
	v_pk_mul_f32 v[56:57], v[56:57], v[82:83] op_sel_hi:[1,0]
	v_pk_mul_f32 v[54:55], v[54:55], v[82:83] op_sel_hi:[1,0]
	v_pk_mul_f32 v[52:53], v[52:53], v[82:83] op_sel_hi:[1,0]
	v_pk_mul_f32 v[50:51], v[50:51], v[82:83] op_sel_hi:[1,0]
	v_pk_mul_f32 v[48:49], v[48:49], v[82:83] op_sel_hi:[1,0]
	v_pk_mul_f32 v[46:47], v[46:47], v[82:83] op_sel_hi:[1,0]
	v_pk_mul_f32 v[44:45], v[44:45], v[82:83] op_sel_hi:[1,0]
	v_pk_mul_f32 v[42:43], v[42:43], v[82:83] op_sel_hi:[1,0]
	v_pk_mul_f32 v[40:41], v[40:41], v[82:83] op_sel_hi:[1,0]
	v_pk_mul_f32 v[38:39], v[38:39], v[82:83] op_sel_hi:[1,0]
	v_pk_mul_f32 v[36:37], v[36:37], v[82:83] op_sel_hi:[1,0]
	v_pk_mul_f32 v[34:35], v[34:35], v[82:83] op_sel_hi:[1,0]
	v_pk_mul_f32 v[32:33], v[32:33], v[82:83] op_sel_hi:[1,0]
	v_pk_mul_f32 v[30:31], v[30:31], v[82:83] op_sel_hi:[1,0]
	v_pk_mul_f32 v[28:29], v[28:29], v[82:83] op_sel_hi:[1,0]
	v_pk_mul_f32 v[26:27], v[26:27], v[82:83] op_sel_hi:[1,0]
	v_pk_mul_f32 v[24:25], v[24:25], v[82:83] op_sel_hi:[1,0]
	v_pk_mul_f32 v[22:23], v[22:23], v[82:83] op_sel_hi:[1,0]
	v_pk_mul_f32 v[20:21], v[20:21], v[82:83] op_sel_hi:[1,0]
	v_pk_mul_f32 v[18:19], v[18:19], v[82:83] op_sel_hi:[1,0]
	v_pk_mul_f32 v[16:17], v[16:17], v[82:83] op_sel_hi:[1,0]
	v_pk_mul_f32 v[14:15], v[14:15], v[82:83] op_sel_hi:[1,0]
	v_pk_mul_f32 v[12:13], v[12:13], v[82:83] op_sel_hi:[1,0]
	v_pk_mul_f32 v[10:11], v[10:11], v[82:83] op_sel_hi:[1,0]
	v_pk_mul_f32 v[8:9], v[8:9], v[82:83] op_sel_hi:[1,0]
	v_pk_mul_f32 v[6:7], v[6:7], v[82:83] op_sel_hi:[1,0]
	v_pk_mul_f32 v[4:5], v[4:5], v[82:83] op_sel_hi:[1,0]
	v_pk_mul_f32 v[2:3], v[2:3], v[82:83] op_sel_hi:[1,0]
	v_pk_mul_f32 v[0:1], v[0:1], v[82:83] op_sel_hi:[1,0]
.LBB0_869:
	v_exp_f32_e32 v96, v96
	v_exp_f32_e32 v97, v97
	v_exp_f32_e32 v98, v98
	s_setprio 1
	v_mfma_f32_32x32x16_bf16 v[80:95], v[248:251], v[144:147], v[64:79]
	ds_read_b128 v[244:247], v220 offset:40960
	v_exp_f32_e32 v99, v99
	v_exp_f32_e32 v100, v100
	v_exp_f32_e32 v101, v101
	v_exp_f32_e32 v102, v102
	v_exp_f32_e32 v103, v103
	v_cvt_pk_bf16_f32 v122, v96, v97
	v_cvt_pk_bf16_f32 v123, v98, v99
	v_mfma_f32_32x32x16_bf16 v[80:95], v[252:255], v[156:159], v[80:95]
	ds_read_b128 v[248:251], v221 offset:40960
	s_add_i32 s4, s8, 4
	s_cmp_ge_u32 s4, s9
	s_cbranch_scc1 .Lmla_dma_skip_t2
	s_add_u32 s98, s34, s60
	s_addc_u32 s99, s35, s59
	s_add_u32 s98, s98, 0x14108000
	s_addc_u32 s99, s99, 0
	s_add_u32 s100, s34, s62
	s_addc_u32 s101, s35, s61
	s_add_u32 s100, s100, 0x171b0200
	s_addc_u32 s101, s101, 0
	s_mov_b32 m0, s46
	s_cmp_lg_u64 s[24:25], 0
	s_cselect_b32 s4, s100, s98
	s_cselect_b32 s5, s101, s99
	global_load_lds_dwordx4 v190, s[4:5]
	s_mov_b32 m0, s47
	s_cmp_lg_u64 s[26:27], 0
	s_cselect_b32 s4, s100, s98
	s_cselect_b32 s5, s101, s99
	global_load_lds_dwordx4 v192, s[4:5]
	s_mov_b32 m0, s48
	s_cmp_lg_u64 s[28:29], 0
	s_cselect_b32 s4, s100, s98
	s_cselect_b32 s5, s101, s99
	global_load_lds_dwordx4 v194, s[4:5]
	s_mov_b32 m0, s49
	s_cmp_lg_u64 s[30:31], 0
	s_cselect_b32 s4, s100, s98
	s_cselect_b32 s5, s101, s99
	global_load_lds_dwordx4 v196, s[4:5]
	s_mov_b32 m0, s50
	s_cmp_lg_u64 s[6:7], 0
	s_cselect_b32 s4, s100, s98
	s_cselect_b32 s5, s101, s99
	global_load_lds_dwordx4 v198, s[4:5]

.LBB0_873:
	v_exp_f32_e32 v113, v80
	v_exp_f32_e32 v126, v85
	v_exp_f32_e32 v127, v86
	s_setprio 1
	v_mfma_f32_32x32x16_bf16 v[96:111], v[244:247], v[144:147], v[64:79]
	ds_read_b128 v[240:243], v220
	v_add_f32_e32 v231, 0, v113
	v_exp_f32_e32 v230, v87
	v_exp_f32_e32 v88, v88
	v_exp_f32_e32 v89, v89
	v_exp_f32_e32 v90, v90
	v_exp_f32_e32 v91, v91
	v_exp_f32_e32 v92, v92
	v_mfma_f32_32x32x16_bf16 v[96:111], v[248:251], v[156:159], v[96:111]
	ds_read_b128 v[244:247], v221
	v_exp_f32_e32 v93, v93
	s_add_u32 s62, s62, 0x180
	s_addc_u32 s61, s61, 0
	s_add_u32 s60, s60, 0x12000
	s_addc_u32 s59, s59, 0
	s_add_i32 s4, s16, 3
	v_mfma_f32_32x32x16_bf16 v[96:111], v[252:255], v[168:171], v[96:111]
	ds_read_b128 v[248:251], v206
	s_cmp_le_u32 s4, s9
	v_mfma_f32_32x32x16_bf16 v[96:111], v[176:179], v[172:175], v[96:111]
	ds_read_b128 v[252:255], v208
	v_mfma_f32_32x32x16_bf16 v[96:111], v[180:183], v[164:167], v[96:111]
	ds_read_b128 v[176:179], v210
	s_waitcnt lgkmcnt(4)
	v_mfma_f32_32x32x16_bf16 v[96:111], v[236:239], v[160:163], v[96:111]
	ds_read_b128 v[180:183], v212
	v_mfma_f32_32x32x16_bf16 v[96:111], v[240:243], v[152:155], v[96:111]
	ds_read_b128 v[236:239], v227 offset:32768
	s_waitcnt lgkmcnt(4)
	v_mfma_f32_32x32x16_bf16 v[96:111], v[244:247], v[148:151], v[96:111]
	ds_read_b128 v[240:243], v227 offset:36864
	v_mfma_f32_32x32x16_bf16 v[96:111], v[248:251], v[140:143], v[96:111]
	ds_read_b128 v[244:247], v227 offset:40960
	s_waitcnt lgkmcnt(4)
	v_mfma_f32_32x32x16_bf16 v[96:111], v[252:255], v[136:139], v[96:111]
	ds_read_b128 v[248:251], v227 offset:45056
	v_exp_f32_e32 v118, v81
	v_exp_f32_e32 v119, v82
	v_exp_f32_e32 v120, v83
	v_exp_f32_e32 v121, v84
	v_mfma_f32_32x32x16_bf16 v[96:111], v[176:179], v[132:135], v[96:111]
	ds_read_b128 v[252:255], v228 offset:36864
	v_cvt_pk_bf16_f32 v114, v113, v118
	v_add_f32_e32 v113, v118, v231
	v_add_f32_e32 v113, v119, v113
	v_add_f32_e32 v113, v120, v113
	v_add_f32_e32 v113, v121, v113
	v_cvt_pk_bf16_f32 v115, v119, v120
	v_cvt_pk_bf16_f32 v116, v121, v126
	v_cvt_pk_bf16_f32 v117, v127, v230
	v_add_f32_e32 v113, v126, v113
	s_waitcnt lgkmcnt(4)
	v_mfma_f32_32x32x16_bf16 v[96:111], v[180:183], v[128:131], v[96:111]
	ds_read_b128 v[176:179], v228 offset:32768
	v_exp_f32_e32 v118, v94
	v_exp_f32_e32 v119, v95
	v_mfma_f32_32x32x16_bf16 v[48:63], v[236:239], v[114:117], v[48:63]
	ds_read_b128 v[180:183], v228 offset:40960
	v_add_f32_e32 v80, v127, v113
	v_add_f32_e32 v80, v230, v80
	v_add_f32_e32 v113, v88, v80
	v_cvt_pk_bf16_f32 v88, v88, v89
	s_waitcnt lgkmcnt(4)
	v_mfma_f32_32x32x16_bf16 v[32:47], v[240:243], v[114:117], v[32:47]
	ds_read_b128 v[236:239], v228 offset:45056
	v_add_f32_e32 v84, v89, v113
	v_add_f32_e32 v84, v90, v84
	v_add_f32_e32 v84, v91, v84
	v_add_f32_e32 v113, v92, v84
	v_add_f32_e32 v113, v93, v113
	v_cvt_pk_bf16_f32 v89, v90, v91
	v_mfma_f32_32x32x16_bf16 v[16:31], v[244:247], v[114:117], v[16:31]
	v_cvt_pk_bf16_f32 v90, v92, v93
	v_cvt_pk_bf16_f32 v91, v118, v119
	s_waitcnt lgkmcnt(3)
	v_mfma_f32_32x32x16_bf16 v[0:15], v[248:251], v[114:117], v[0:15]
	v_max_f32_e32 v114, v97, v97
	v_max_f32_e32 v115, v96, v96
	v_max_f32_e32 v114, v115, v114
	v_max3_f32 v114, v114, v98, v99
	v_mfma_f32_32x32x16_bf16 v[32:47], v[252:255], v[88:91], v[32:47]
	s_waitcnt vmcnt(0)
	s_barrier
	s_waitcnt lgkmcnt(2)
	v_mfma_f32_32x32x16_bf16 v[48:63], v[176:179], v[88:91], v[48:63]
	v_max3_f32 v80, v114, v100, v101
	v_max3_f32 v80, v80, v102, v103
	v_max3_f32 v80, v80, v104, v105
	v_max3_f32 v80, v80, v106, v107
	v_max3_f32 v80, v80, v108, v109
	v_max3_f32 v80, v80, v110, v111
	ds_bpermute_b32 v81, v229, v80
	s_waitcnt lgkmcnt(2)
	v_mfma_f32_32x32x16_bf16 v[16:31], v[180:183], v[88:91], v[16:31]
	v_add_f32_e32 v82, v118, v113
	v_add_f32_e32 v82, v119, v82
	v_add_f32_e32 v230, v112, v82
	s_waitcnt lgkmcnt(0)
	v_max_f32_e32 v81, v81, v81
	v_max_f32_e32 v82, v80, v81
	v_mfma_f32_32x32x16_bf16 v[0:15], v[236:239], v[88:91], v[0:15]
	s_setprio 0
	s_cbranch_scc0 .LBB0_875
	s_mov_b32 s8, s16
	v_cmp_lt_f32_e32 vcc, 0, v82
	s_cbranch_vccnz .LBB0_858
	s_branch .LBB0_859
